# sample unit compressed-key score loop unrolled x4, 12 of 16 row loads in flight up front (three rotating register sets) instead of 8 serial round trips
# baseline (speedup 1.0000x reference)
.LBB0_2289:
	v_add_co_u32_e32 v10, vcc, 0x6600000, v8
	s_nop 1
	v_addc_co_u32_e32 v11, vcc, 0, v9, vcc
	global_load_dwordx4 v[76:79], v[10:11], off
	global_load_dwordx4 v[80:83], v[10:11], off offset:16
	global_load_dwordx4 v[84:87], v[10:11], off offset:32
	global_load_dwordx4 v[88:91], v[10:11], off offset:48
	global_load_dwordx4 v[230:233], v[10:11], off offset:64
	global_load_dwordx4 v[234:237], v[10:11], off offset:80
	global_load_dwordx4 v[238:241], v[10:11], off offset:96
	global_load_dwordx4 v[242:245], v[10:11], off offset:112
	global_load_dwordx4 v[246:249], v[10:11], off offset:128
	global_load_dwordx4 v[250:253], v[10:11], off offset:144
	global_load_dwordx4 v[110:113], v[10:11], off offset:160
	global_load_dwordx4 v[114:117], v[10:11], off offset:176
	v_mov_b32_e32 v3, s12
	ds_read_b128 v[12:15], v3
	ds_read_b128 v[16:19], v3 offset:16
	ds_read_b128 v[20:23], v3 offset:32
	ds_read_b128 v[24:27], v3 offset:48
	ds_read_b128 v[28:31], v3 offset:256
	ds_read_b128 v[32:35], v3 offset:272
	ds_read_b128 v[36:39], v3 offset:512
	ds_read_b128 v[40:43], v3 offset:528
	ds_read_b128 v[44:47], v3 offset:768
	ds_read_b128 v[48:51], v3 offset:784
	ds_read_b128 v[52:55], v3 offset:288
	ds_read_b128 v[56:59], v3 offset:304
	ds_read_b128 v[60:63], v3 offset:544
	ds_read_b128 v[64:67], v3 offset:560
	ds_read_b128 v[68:71], v3 offset:800
	ds_read_b128 v[72:75], v3 offset:816
	s_waitcnt vmcnt(8)
	s_waitcnt lgkmcnt(0)
	v_mov_b32_e32 v10, v28
	v_mov_b32_e32 v11, v13
	v_mov_b32_e32 v28, v29
	v_mov_b32_e32 v29, v12
	v_mov_b32_e32 v12, v30
	v_mov_b32_e32 v13, v14
	v_mov_b32_e32 v14, v31
	v_mov_b32_e32 v30, v44
	v_mov_b32_e32 v31, v37
	v_mov_b32_e32 v44, v45
	v_mov_b32_e32 v45, v36
	v_mov_b32_e32 v36, v46
	v_mov_b32_e32 v37, v38
	v_mov_b32_e32 v38, v47
	v_mov_b32_e32 v46, v32
	v_mov_b32_e32 v47, v17
	v_mov_b32_e32 v32, v33
	v_mov_b32_e32 v33, v16
	v_mov_b32_e32 v16, v34
	v_mov_b32_e32 v17, v18
	v_mov_b32_e32 v18, v35
	v_mov_b32_e32 v34, v48
	v_mov_b32_e32 v35, v41
	v_mov_b32_e32 v48, v49
	v_mov_b32_e32 v49, v40
	v_mov_b32_e32 v40, v50
	v_mov_b32_e32 v41, v42
	v_mov_b32_e32 v42, v51
	v_mov_b32_e32 v50, v52
	v_mov_b32_e32 v51, v21
	v_mov_b32_e32 v52, v53
	v_mov_b32_e32 v53, v20
	v_mov_b32_e32 v20, v54
	v_mov_b32_e32 v21, v22
	v_mov_b32_e32 v22, v55
	v_mov_b32_e32 v54, v68
	v_mov_b32_e32 v55, v61
	v_mov_b32_e32 v68, v69
	v_mov_b32_e32 v69, v60
	v_mov_b32_e32 v60, v70
	v_mov_b32_e32 v61, v62
	v_mov_b32_e32 v62, v71
	v_mov_b32_e32 v70, v56
	v_mov_b32_e32 v71, v25
	v_mov_b32_e32 v56, v57
	v_mov_b32_e32 v57, v24
	v_mov_b32_e32 v24, v58
	v_mov_b32_e32 v25, v26
	v_mov_b32_e32 v26, v59
	v_mov_b32_e32 v58, v72
	v_mov_b32_e32 v59, v65
	v_mov_b32_e32 v72, v73
	v_mov_b32_e32 v73, v64
	v_mov_b32_e32 v64, v74
	s_add_i32 s12, s12, 64
	v_mov_b32_e32 v65, v66
	v_mov_b32_e32 v66, v75
	v_pk_mul_f32 v[10:11], v[76:77], v[10:11]
	v_pk_mul_f32 v[30:31], v[76:77], v[30:31]
	v_pk_mul_f32 v[46:47], v[80:81], v[46:47]
	v_pk_mul_f32 v[34:35], v[80:81], v[34:35]
	v_pk_fma_f32 v[10:11], v[76:77], v[28:29], v[10:11] op_sel:[1,0,0] op_sel_hi:[0,1,1]
	v_pk_fma_f32 v[28:29], v[76:77], v[44:45], v[30:31] op_sel:[1,0,0] op_sel_hi:[0,1,1]
	v_mov_b32_e32 v74, v79
	v_pk_mul_f32 v[50:51], v[84:85], v[50:51]
	v_pk_mul_f32 v[54:55], v[84:85], v[54:55]
	v_pk_fma_f32 v[30:31], v[80:81], v[32:33], v[46:47] op_sel:[1,0,0] op_sel_hi:[0,1,1]
	v_pk_fma_f32 v[32:33], v[80:81], v[48:49], v[34:35] op_sel:[1,0,0] op_sel_hi:[0,1,1]
	v_pk_fma_f32 v[10:11], v[78:79], v[12:13], v[10:11] op_sel_hi:[0,1,1]
	v_pk_fma_f32 v[12:13], v[78:79], v[36:37], v[28:29] op_sel_hi:[0,1,1]
	v_mov_b32_e32 v92, v83
	v_pk_mul_f32 v[70:71], v[88:89], v[70:71]
	v_pk_mul_f32 v[58:59], v[88:89], v[58:59]
	v_pk_fma_f32 v[34:35], v[84:85], v[52:53], v[50:51] op_sel:[1,0,0] op_sel_hi:[0,1,1]
	v_pk_fma_f32 v[44:45], v[84:85], v[68:69], v[54:55] op_sel:[1,0,0] op_sel_hi:[0,1,1]
	v_pk_fma_f32 v[16:17], v[82:83], v[16:17], v[30:31] op_sel_hi:[0,1,1]
	v_pk_fma_f32 v[28:29], v[82:83], v[40:41], v[32:33] op_sel_hi:[0,1,1]
	v_pk_fma_f32 v[10:11], v[74:75], v[14:15], v[10:11] op_sel_hi:[0,1,1]
	v_pk_fma_f32 v[12:13], v[74:75], v[38:39], v[12:13] op_sel_hi:[0,1,1]
	v_mov_b32_e32 v94, v87
	v_pk_fma_f32 v[46:47], v[88:89], v[56:57], v[70:71] op_sel:[1,0,0] op_sel_hi:[0,1,1]
	v_pk_fma_f32 v[48:49], v[88:89], v[72:73], v[58:59] op_sel:[1,0,0] op_sel_hi:[0,1,1]
	v_pk_fma_f32 v[20:21], v[86:87], v[20:21], v[34:35] op_sel_hi:[0,1,1]
	v_pk_fma_f32 v[30:31], v[86:87], v[60:61], v[44:45] op_sel_hi:[0,1,1]
	v_pk_fma_f32 v[14:15], v[92:93], v[18:19], v[16:17] op_sel_hi:[0,1,1]
	v_pk_fma_f32 v[16:17], v[92:93], v[42:43], v[28:29] op_sel_hi:[0,1,1]
	v_pk_add_f32 v[6:7], v[6:7], v[10:11]
	v_pk_add_f32 v[4:5], v[4:5], v[12:13]
	v_mov_b32_e32 v96, v91
	v_pk_fma_f32 v[24:25], v[90:91], v[24:25], v[46:47] op_sel_hi:[0,1,1]
	v_pk_fma_f32 v[32:33], v[90:91], v[64:65], v[48:49] op_sel_hi:[0,1,1]
	v_pk_fma_f32 v[18:19], v[94:95], v[22:23], v[20:21] op_sel_hi:[0,1,1]
	v_pk_fma_f32 v[20:21], v[94:95], v[62:63], v[30:31] op_sel_hi:[0,1,1]
	v_pk_add_f32 v[6:7], v[6:7], v[14:15]
	v_pk_add_f32 v[4:5], v[4:5], v[16:17]
	v_pk_fma_f32 v[22:23], v[96:97], v[26:27], v[24:25] op_sel_hi:[0,1,1]
	v_pk_fma_f32 v[24:25], v[96:97], v[66:67], v[32:33] op_sel_hi:[0,1,1]
	v_pk_add_f32 v[6:7], v[6:7], v[18:19]
	v_pk_add_f32 v[4:5], v[4:5], v[20:21]
	v_pk_add_f32 v[6:7], v[6:7], v[22:23]
	v_pk_add_f32 v[4:5], v[4:5], v[24:25]
	v_add_co_u32_e32 v76, vcc, 0x6600000, v8
	s_nop 1
	v_addc_co_u32_e32 v77, vcc, 0, v9, vcc
	global_load_dwordx4 v[80:83], v[76:77], off offset:208
	global_load_dwordx4 v[84:87], v[76:77], off offset:224
	global_load_dwordx4 v[88:91], v[76:77], off offset:240
	global_load_dwordx4 v[76:79], v[76:77], off offset:192
	v_mov_b32_e32 v3, s12
	ds_read_b128 v[12:15], v3
	ds_read_b128 v[16:19], v3 offset:16
	ds_read_b128 v[20:23], v3 offset:32
	ds_read_b128 v[24:27], v3 offset:48
	ds_read_b128 v[28:31], v3 offset:256
	ds_read_b128 v[32:35], v3 offset:272
	ds_read_b128 v[36:39], v3 offset:512
	ds_read_b128 v[40:43], v3 offset:528
	ds_read_b128 v[44:47], v3 offset:768
	ds_read_b128 v[48:51], v3 offset:784
	ds_read_b128 v[52:55], v3 offset:288
	ds_read_b128 v[56:59], v3 offset:304
	ds_read_b128 v[60:63], v3 offset:544
	ds_read_b128 v[64:67], v3 offset:560
	ds_read_b128 v[68:71], v3 offset:800
	ds_read_b128 v[72:75], v3 offset:816
	s_waitcnt vmcnt(8)
	s_waitcnt lgkmcnt(0)
	v_mov_b32_e32 v10, v28
	v_mov_b32_e32 v11, v13
	v_mov_b32_e32 v28, v29
	v_mov_b32_e32 v29, v12
	v_mov_b32_e32 v12, v30
	v_mov_b32_e32 v13, v14
	v_mov_b32_e32 v14, v31
	v_mov_b32_e32 v30, v44
	v_mov_b32_e32 v31, v37
	v_mov_b32_e32 v44, v45
	v_mov_b32_e32 v45, v36
	v_mov_b32_e32 v36, v46
	v_mov_b32_e32 v37, v38
	v_mov_b32_e32 v38, v47
	v_mov_b32_e32 v46, v32
	v_mov_b32_e32 v47, v17
	v_mov_b32_e32 v32, v33
	v_mov_b32_e32 v33, v16
	v_mov_b32_e32 v16, v34
	v_mov_b32_e32 v17, v18
	v_mov_b32_e32 v18, v35
	v_mov_b32_e32 v34, v48
	v_mov_b32_e32 v35, v41
	v_mov_b32_e32 v48, v49
	v_mov_b32_e32 v49, v40
	v_mov_b32_e32 v40, v50
	v_mov_b32_e32 v41, v42
	v_mov_b32_e32 v42, v51
	v_mov_b32_e32 v50, v52
	v_mov_b32_e32 v51, v21
	v_mov_b32_e32 v52, v53
	v_mov_b32_e32 v53, v20
	v_mov_b32_e32 v20, v54
	v_mov_b32_e32 v21, v22
	v_mov_b32_e32 v22, v55
	v_mov_b32_e32 v54, v68
	v_mov_b32_e32 v55, v61
	v_mov_b32_e32 v68, v69
	v_mov_b32_e32 v69, v60
	v_mov_b32_e32 v60, v70
	v_mov_b32_e32 v61, v62
	v_mov_b32_e32 v62, v71
	v_mov_b32_e32 v70, v56
	v_mov_b32_e32 v71, v25
	v_mov_b32_e32 v56, v57
	v_mov_b32_e32 v57, v24
	v_mov_b32_e32 v24, v58
	v_mov_b32_e32 v25, v26
	v_mov_b32_e32 v26, v59
	v_mov_b32_e32 v58, v72
	v_mov_b32_e32 v59, v65
	v_mov_b32_e32 v72, v73
	v_mov_b32_e32 v73, v64
	v_mov_b32_e32 v64, v74
	s_add_i32 s12, s12, 64
	v_mov_b32_e32 v65, v66
	v_mov_b32_e32 v66, v75
	v_pk_mul_f32 v[10:11], v[230:231], v[10:11]
	v_pk_mul_f32 v[30:31], v[230:231], v[30:31]
	v_pk_mul_f32 v[46:47], v[234:235], v[46:47]
	v_pk_mul_f32 v[34:35], v[234:235], v[34:35]
	v_pk_fma_f32 v[10:11], v[230:231], v[28:29], v[10:11] op_sel:[1,0,0] op_sel_hi:[0,1,1]
	v_pk_fma_f32 v[28:29], v[230:231], v[44:45], v[30:31] op_sel:[1,0,0] op_sel_hi:[0,1,1]
	v_mov_b32_e32 v74, v233
	v_pk_mul_f32 v[50:51], v[238:239], v[50:51]
	v_pk_mul_f32 v[54:55], v[238:239], v[54:55]
	v_pk_fma_f32 v[30:31], v[234:235], v[32:33], v[46:47] op_sel:[1,0,0] op_sel_hi:[0,1,1]
	v_pk_fma_f32 v[32:33], v[234:235], v[48:49], v[34:35] op_sel:[1,0,0] op_sel_hi:[0,1,1]
	v_pk_fma_f32 v[10:11], v[232:233], v[12:13], v[10:11] op_sel_hi:[0,1,1]
	v_pk_fma_f32 v[12:13], v[232:233], v[36:37], v[28:29] op_sel_hi:[0,1,1]
	v_mov_b32_e32 v92, v237
	v_pk_mul_f32 v[70:71], v[242:243], v[70:71]
	v_pk_mul_f32 v[58:59], v[242:243], v[58:59]
	v_pk_fma_f32 v[34:35], v[238:239], v[52:53], v[50:51] op_sel:[1,0,0] op_sel_hi:[0,1,1]
	v_pk_fma_f32 v[44:45], v[238:239], v[68:69], v[54:55] op_sel:[1,0,0] op_sel_hi:[0,1,1]
	v_pk_fma_f32 v[16:17], v[236:237], v[16:17], v[30:31] op_sel_hi:[0,1,1]
	v_pk_fma_f32 v[28:29], v[236:237], v[40:41], v[32:33] op_sel_hi:[0,1,1]
	v_pk_fma_f32 v[10:11], v[74:75], v[14:15], v[10:11] op_sel_hi:[0,1,1]
	v_pk_fma_f32 v[12:13], v[74:75], v[38:39], v[12:13] op_sel_hi:[0,1,1]
	v_mov_b32_e32 v94, v241
	v_pk_fma_f32 v[46:47], v[242:243], v[56:57], v[70:71] op_sel:[1,0,0] op_sel_hi:[0,1,1]
	v_pk_fma_f32 v[48:49], v[242:243], v[72:73], v[58:59] op_sel:[1,0,0] op_sel_hi:[0,1,1]
	v_pk_fma_f32 v[20:21], v[240:241], v[20:21], v[34:35] op_sel_hi:[0,1,1]
	v_pk_fma_f32 v[30:31], v[240:241], v[60:61], v[44:45] op_sel_hi:[0,1,1]
	v_pk_fma_f32 v[14:15], v[92:93], v[18:19], v[16:17] op_sel_hi:[0,1,1]
	v_pk_fma_f32 v[16:17], v[92:93], v[42:43], v[28:29] op_sel_hi:[0,1,1]
	v_pk_add_f32 v[6:7], v[6:7], v[10:11]
	v_pk_add_f32 v[4:5], v[4:5], v[12:13]
	v_mov_b32_e32 v96, v245
	v_pk_fma_f32 v[24:25], v[244:245], v[24:25], v[46:47] op_sel_hi:[0,1,1]
	v_pk_fma_f32 v[32:33], v[244:245], v[64:65], v[48:49] op_sel_hi:[0,1,1]
	v_pk_fma_f32 v[18:19], v[94:95], v[22:23], v[20:21] op_sel_hi:[0,1,1]
	v_pk_fma_f32 v[20:21], v[94:95], v[62:63], v[30:31] op_sel_hi:[0,1,1]
	v_pk_add_f32 v[6:7], v[6:7], v[14:15]
	v_pk_add_f32 v[4:5], v[4:5], v[16:17]
	v_pk_fma_f32 v[22:23], v[96:97], v[26:27], v[24:25] op_sel_hi:[0,1,1]
	v_pk_fma_f32 v[24:25], v[96:97], v[66:67], v[32:33] op_sel_hi:[0,1,1]
	v_pk_add_f32 v[6:7], v[6:7], v[18:19]
	v_pk_add_f32 v[4:5], v[4:5], v[20:21]
	v_pk_add_f32 v[6:7], v[6:7], v[22:23]
	v_pk_add_f32 v[4:5], v[4:5], v[24:25]
	v_mov_b32_e32 v3, s12
	ds_read_b128 v[12:15], v3
	ds_read_b128 v[16:19], v3 offset:16
	ds_read_b128 v[20:23], v3 offset:32
	ds_read_b128 v[24:27], v3 offset:48
	ds_read_b128 v[28:31], v3 offset:256
	ds_read_b128 v[32:35], v3 offset:272
	ds_read_b128 v[36:39], v3 offset:512
	ds_read_b128 v[40:43], v3 offset:528
	ds_read_b128 v[44:47], v3 offset:768
	ds_read_b128 v[48:51], v3 offset:784
	ds_read_b128 v[52:55], v3 offset:288
	ds_read_b128 v[56:59], v3 offset:304
	ds_read_b128 v[60:63], v3 offset:544
	ds_read_b128 v[64:67], v3 offset:560
	ds_read_b128 v[68:71], v3 offset:800
	ds_read_b128 v[72:75], v3 offset:816
	s_waitcnt vmcnt(4)
	s_waitcnt lgkmcnt(0)
	v_mov_b32_e32 v10, v28
	v_mov_b32_e32 v11, v13
	v_mov_b32_e32 v28, v29
	v_mov_b32_e32 v29, v12
	v_mov_b32_e32 v12, v30
	v_mov_b32_e32 v13, v14
	v_mov_b32_e32 v14, v31
	v_mov_b32_e32 v30, v44
	v_mov_b32_e32 v31, v37
	v_mov_b32_e32 v44, v45
	v_mov_b32_e32 v45, v36
	v_mov_b32_e32 v36, v46
	v_mov_b32_e32 v37, v38
	v_mov_b32_e32 v38, v47
	v_mov_b32_e32 v46, v32
	v_mov_b32_e32 v47, v17
	v_mov_b32_e32 v32, v33
	v_mov_b32_e32 v33, v16
	v_mov_b32_e32 v16, v34
	v_mov_b32_e32 v17, v18
	v_mov_b32_e32 v18, v35
	v_mov_b32_e32 v34, v48
	v_mov_b32_e32 v35, v41
	v_mov_b32_e32 v48, v49
	v_mov_b32_e32 v49, v40
	v_mov_b32_e32 v40, v50
	v_mov_b32_e32 v41, v42
	v_mov_b32_e32 v42, v51
	v_mov_b32_e32 v50, v52
	v_mov_b32_e32 v51, v21
	v_mov_b32_e32 v52, v53
	v_mov_b32_e32 v53, v20
	v_mov_b32_e32 v20, v54
	v_mov_b32_e32 v21, v22
	v_mov_b32_e32 v22, v55
	v_mov_b32_e32 v54, v68
	v_mov_b32_e32 v55, v61
	v_mov_b32_e32 v68, v69
	v_mov_b32_e32 v69, v60
	v_mov_b32_e32 v60, v70
	v_mov_b32_e32 v61, v62
	v_mov_b32_e32 v62, v71
	v_mov_b32_e32 v70, v56
	v_mov_b32_e32 v71, v25
	v_mov_b32_e32 v56, v57
	v_mov_b32_e32 v57, v24
	v_mov_b32_e32 v24, v58
	v_mov_b32_e32 v25, v26
	v_mov_b32_e32 v26, v59
	v_mov_b32_e32 v58, v72
	v_mov_b32_e32 v59, v65
	v_mov_b32_e32 v72, v73
	v_mov_b32_e32 v73, v64
	v_mov_b32_e32 v64, v74
	s_add_i32 s12, s12, 64
	v_mov_b32_e32 v65, v66
	v_mov_b32_e32 v66, v75
	v_pk_mul_f32 v[10:11], v[246:247], v[10:11]
	v_pk_mul_f32 v[30:31], v[246:247], v[30:31]
	v_pk_mul_f32 v[46:47], v[250:251], v[46:47]
	v_pk_mul_f32 v[34:35], v[250:251], v[34:35]
	v_pk_fma_f32 v[10:11], v[246:247], v[28:29], v[10:11] op_sel:[1,0,0] op_sel_hi:[0,1,1]
	v_pk_fma_f32 v[28:29], v[246:247], v[44:45], v[30:31] op_sel:[1,0,0] op_sel_hi:[0,1,1]
	v_mov_b32_e32 v74, v249
	v_pk_mul_f32 v[50:51], v[110:111], v[50:51]
	v_pk_mul_f32 v[54:55], v[110:111], v[54:55]
	v_pk_fma_f32 v[30:31], v[250:251], v[32:33], v[46:47] op_sel:[1,0,0] op_sel_hi:[0,1,1]
	v_pk_fma_f32 v[32:33], v[250:251], v[48:49], v[34:35] op_sel:[1,0,0] op_sel_hi:[0,1,1]
	v_pk_fma_f32 v[10:11], v[248:249], v[12:13], v[10:11] op_sel_hi:[0,1,1]
	v_pk_fma_f32 v[12:13], v[248:249], v[36:37], v[28:29] op_sel_hi:[0,1,1]
	v_mov_b32_e32 v92, v253
	v_pk_mul_f32 v[70:71], v[114:115], v[70:71]
	v_pk_mul_f32 v[58:59], v[114:115], v[58:59]
	v_pk_fma_f32 v[34:35], v[110:111], v[52:53], v[50:51] op_sel:[1,0,0] op_sel_hi:[0,1,1]
	v_pk_fma_f32 v[44:45], v[110:111], v[68:69], v[54:55] op_sel:[1,0,0] op_sel_hi:[0,1,1]
	v_pk_fma_f32 v[16:17], v[252:253], v[16:17], v[30:31] op_sel_hi:[0,1,1]
	v_pk_fma_f32 v[28:29], v[252:253], v[40:41], v[32:33] op_sel_hi:[0,1,1]
	v_pk_fma_f32 v[10:11], v[74:75], v[14:15], v[10:11] op_sel_hi:[0,1,1]
	v_pk_fma_f32 v[12:13], v[74:75], v[38:39], v[12:13] op_sel_hi:[0,1,1]
	v_mov_b32_e32 v94, v113
	v_pk_fma_f32 v[46:47], v[114:115], v[56:57], v[70:71] op_sel:[1,0,0] op_sel_hi:[0,1,1]
	v_pk_fma_f32 v[48:49], v[114:115], v[72:73], v[58:59] op_sel:[1,0,0] op_sel_hi:[0,1,1]
	v_pk_fma_f32 v[20:21], v[112:113], v[20:21], v[34:35] op_sel_hi:[0,1,1]
	v_pk_fma_f32 v[30:31], v[112:113], v[60:61], v[44:45] op_sel_hi:[0,1,1]
	v_pk_fma_f32 v[14:15], v[92:93], v[18:19], v[16:17] op_sel_hi:[0,1,1]
	v_pk_fma_f32 v[16:17], v[92:93], v[42:43], v[28:29] op_sel_hi:[0,1,1]
	v_pk_add_f32 v[6:7], v[6:7], v[10:11]
	v_pk_add_f32 v[4:5], v[4:5], v[12:13]
	v_mov_b32_e32 v96, v117
	v_pk_fma_f32 v[24:25], v[116:117], v[24:25], v[46:47] op_sel_hi:[0,1,1]
	v_pk_fma_f32 v[32:33], v[116:117], v[64:65], v[48:49] op_sel_hi:[0,1,1]
	v_pk_fma_f32 v[18:19], v[94:95], v[22:23], v[20:21] op_sel_hi:[0,1,1]
	v_pk_fma_f32 v[20:21], v[94:95], v[62:63], v[30:31] op_sel_hi:[0,1,1]
	v_pk_add_f32 v[6:7], v[6:7], v[14:15]
	v_pk_add_f32 v[4:5], v[4:5], v[16:17]
	v_pk_fma_f32 v[22:23], v[96:97], v[26:27], v[24:25] op_sel_hi:[0,1,1]
	v_pk_fma_f32 v[24:25], v[96:97], v[66:67], v[32:33] op_sel_hi:[0,1,1]
	v_pk_add_f32 v[6:7], v[6:7], v[18:19]
	v_pk_add_f32 v[4:5], v[4:5], v[20:21]
	v_pk_add_f32 v[6:7], v[6:7], v[22:23]
	v_pk_add_f32 v[4:5], v[4:5], v[24:25]
	v_mov_b32_e32 v3, s12
	ds_read_b128 v[12:15], v3
	ds_read_b128 v[16:19], v3 offset:16
	ds_read_b128 v[20:23], v3 offset:32
	ds_read_b128 v[24:27], v3 offset:48
	ds_read_b128 v[28:31], v3 offset:256
	ds_read_b128 v[32:35], v3 offset:272
	ds_read_b128 v[36:39], v3 offset:512
	ds_read_b128 v[40:43], v3 offset:528
	ds_read_b128 v[44:47], v3 offset:768
	ds_read_b128 v[48:51], v3 offset:784
	ds_read_b128 v[52:55], v3 offset:288
	ds_read_b128 v[56:59], v3 offset:304
	ds_read_b128 v[60:63], v3 offset:544
	ds_read_b128 v[64:67], v3 offset:560
	ds_read_b128 v[68:71], v3 offset:800
	ds_read_b128 v[72:75], v3 offset:816
	s_waitcnt vmcnt(0)
	s_waitcnt lgkmcnt(0)
	v_mov_b32_e32 v10, v28
	v_mov_b32_e32 v11, v13
	v_mov_b32_e32 v28, v29
	v_mov_b32_e32 v29, v12
	v_mov_b32_e32 v12, v30
	v_mov_b32_e32 v13, v14
	v_mov_b32_e32 v14, v31
	v_mov_b32_e32 v30, v44
	v_mov_b32_e32 v31, v37
	v_mov_b32_e32 v44, v45
	v_mov_b32_e32 v45, v36
	v_mov_b32_e32 v36, v46
	v_mov_b32_e32 v37, v38
	v_mov_b32_e32 v38, v47
	v_mov_b32_e32 v46, v32
	v_mov_b32_e32 v47, v17
	v_mov_b32_e32 v32, v33
	v_mov_b32_e32 v33, v16
	v_mov_b32_e32 v16, v34
	v_mov_b32_e32 v17, v18
	v_mov_b32_e32 v18, v35
	v_mov_b32_e32 v34, v48
	v_mov_b32_e32 v35, v41
	v_mov_b32_e32 v48, v49
	v_mov_b32_e32 v49, v40
	v_mov_b32_e32 v40, v50
	v_mov_b32_e32 v41, v42
	v_mov_b32_e32 v42, v51
	v_mov_b32_e32 v50, v52
	v_mov_b32_e32 v51, v21
	v_mov_b32_e32 v52, v53
	v_mov_b32_e32 v53, v20
	v_mov_b32_e32 v20, v54
	v_mov_b32_e32 v21, v22
	v_mov_b32_e32 v22, v55
	v_mov_b32_e32 v54, v68
	v_mov_b32_e32 v55, v61
	v_mov_b32_e32 v68, v69
	v_mov_b32_e32 v69, v60
	v_mov_b32_e32 v60, v70
	v_mov_b32_e32 v61, v62
	v_mov_b32_e32 v62, v71
	v_mov_b32_e32 v70, v56
	v_mov_b32_e32 v71, v25
	v_mov_b32_e32 v56, v57
	v_mov_b32_e32 v57, v24
	v_mov_b32_e32 v24, v58
	v_mov_b32_e32 v25, v26
	v_mov_b32_e32 v26, v59
	v_mov_b32_e32 v58, v72
	v_mov_b32_e32 v59, v65
	v_mov_b32_e32 v72, v73
	v_mov_b32_e32 v73, v64
	v_mov_b32_e32 v64, v74
	s_add_i32 s12, s12, 64
	v_mov_b32_e32 v65, v66
	v_mov_b32_e32 v66, v75
	v_pk_mul_f32 v[10:11], v[76:77], v[10:11]
	v_pk_mul_f32 v[30:31], v[76:77], v[30:31]
	v_pk_mul_f32 v[46:47], v[80:81], v[46:47]
	v_pk_mul_f32 v[34:35], v[80:81], v[34:35]
	v_pk_fma_f32 v[10:11], v[76:77], v[28:29], v[10:11] op_sel:[1,0,0] op_sel_hi:[0,1,1]
	v_pk_fma_f32 v[28:29], v[76:77], v[44:45], v[30:31] op_sel:[1,0,0] op_sel_hi:[0,1,1]
	v_mov_b32_e32 v74, v79
	v_pk_mul_f32 v[50:51], v[84:85], v[50:51]
	v_pk_mul_f32 v[54:55], v[84:85], v[54:55]
	v_pk_fma_f32 v[30:31], v[80:81], v[32:33], v[46:47] op_sel:[1,0,0] op_sel_hi:[0,1,1]
	v_pk_fma_f32 v[32:33], v[80:81], v[48:49], v[34:35] op_sel:[1,0,0] op_sel_hi:[0,1,1]
	v_pk_fma_f32 v[10:11], v[78:79], v[12:13], v[10:11] op_sel_hi:[0,1,1]
	v_pk_fma_f32 v[12:13], v[78:79], v[36:37], v[28:29] op_sel_hi:[0,1,1]
	v_mov_b32_e32 v92, v83
	v_pk_mul_f32 v[70:71], v[88:89], v[70:71]
	v_pk_mul_f32 v[58:59], v[88:89], v[58:59]
	v_pk_fma_f32 v[34:35], v[84:85], v[52:53], v[50:51] op_sel:[1,0,0] op_sel_hi:[0,1,1]
	v_pk_fma_f32 v[44:45], v[84:85], v[68:69], v[54:55] op_sel:[1,0,0] op_sel_hi:[0,1,1]
	v_pk_fma_f32 v[16:17], v[82:83], v[16:17], v[30:31] op_sel_hi:[0,1,1]
	v_pk_fma_f32 v[28:29], v[82:83], v[40:41], v[32:33] op_sel_hi:[0,1,1]
	v_pk_fma_f32 v[10:11], v[74:75], v[14:15], v[10:11] op_sel_hi:[0,1,1]
	v_pk_fma_f32 v[12:13], v[74:75], v[38:39], v[12:13] op_sel_hi:[0,1,1]
	v_mov_b32_e32 v94, v87
	v_pk_fma_f32 v[46:47], v[88:89], v[56:57], v[70:71] op_sel:[1,0,0] op_sel_hi:[0,1,1]
	v_pk_fma_f32 v[48:49], v[88:89], v[72:73], v[58:59] op_sel:[1,0,0] op_sel_hi:[0,1,1]
	v_pk_fma_f32 v[20:21], v[86:87], v[20:21], v[34:35] op_sel_hi:[0,1,1]
	v_pk_fma_f32 v[30:31], v[86:87], v[60:61], v[44:45] op_sel_hi:[0,1,1]
	v_pk_fma_f32 v[14:15], v[92:93], v[18:19], v[16:17] op_sel_hi:[0,1,1]
	v_pk_fma_f32 v[16:17], v[92:93], v[42:43], v[28:29] op_sel_hi:[0,1,1]
	v_pk_add_f32 v[6:7], v[6:7], v[10:11]
	v_pk_add_f32 v[4:5], v[4:5], v[12:13]
	v_mov_b32_e32 v96, v91
	v_pk_fma_f32 v[24:25], v[90:91], v[24:25], v[46:47] op_sel_hi:[0,1,1]
	v_pk_fma_f32 v[32:33], v[90:91], v[64:65], v[48:49] op_sel_hi:[0,1,1]
	v_pk_fma_f32 v[18:19], v[94:95], v[22:23], v[20:21] op_sel_hi:[0,1,1]
	v_pk_fma_f32 v[20:21], v[94:95], v[62:63], v[30:31] op_sel_hi:[0,1,1]
	v_pk_add_f32 v[6:7], v[6:7], v[14:15]
	v_pk_add_f32 v[4:5], v[4:5], v[16:17]
	v_pk_fma_f32 v[22:23], v[96:97], v[26:27], v[24:25] op_sel_hi:[0,1,1]
	v_pk_fma_f32 v[24:25], v[96:97], v[66:67], v[32:33] op_sel_hi:[0,1,1]
	v_pk_add_f32 v[6:7], v[6:7], v[18:19]
	v_pk_add_f32 v[4:5], v[4:5], v[20:21]
	v_pk_add_f32 v[6:7], v[6:7], v[22:23]
	v_pk_add_f32 v[4:5], v[4:5], v[24:25]
	s_mov_b64 s[10:11], 0x100
